# select exact-split emit: indices staged in a 512-byte per-wave LDS list, one coalesced store per query (replaces up to 64 scattered 2-byte stores)
# baseline (speedup 1.0000x reference)
; template <class T> __device__ __forceinline__ T launder(T p) { asm volatile("" : "+s"(p)); return p; }
; __device__ __forceinline__ int otid() { int t = threadIdx.x; asm volatile("" : "+v"(t)); return t; }
; __device__ __forceinline__ void select_group(unsigned char* ws, int r0, const bf16_t* __restrict__ kib, int n, float* sc, SelPre& pre, int nr0, const bf16_t* __restrict__ nkib, int nn) {
;   const int tid = otid(), lane = tid & 63, w = tid >> 6;
; __device__ __forceinline__ void phase_select(KP kp, int l, unsigned char* shm) {
;   kp = launder(kp);
;   float* sc = (float*)shm;
;   unsigned char* ws = kp->ws;
;   const int tid = otid(), lane = tid & 63, w = tid >> 6;
;   for (int tile0 = blockIdx.x; tile0 < 272; tile0 += gridDim.x) {
;     const int tile = tile0 < 256 ? (tile0 & 7) * 32 + (tile0 >> 3) : tile0;
;     const int ng = tile >= 256 ? 4 : 16;
;     SelPre pre;
.LBB0_2882:
	s_or_b64 exec, exec, s[0:1]
	v_readlane_b32 s2, v254, 13
	v_readlane_b32 s0, v254, 2
	v_readlane_b32 s3, v254, 14
	v_readlane_b32 s1, v254, 3
	s_waitcnt lgkmcnt(0)
	v_mov_b32_e32 v0, v244
	s_and_b64 vcc, exec, s[2:3]
	s_barrier
	s_cbranch_vccz .LBB0_3394
	s_load_dwordx2 s[0:1], s[0:1], 0xb0
	v_ashrrev_i32_e32 v198, 6, v0
	v_and_b32_e32 v2, 63, v0
	v_bfe_u32 v196, v0, 5, 1
	v_bfe_u32 v197, v0, 2, 3
	s_waitcnt lgkmcnt(0)
	s_add_u32 s2, s0, 0x1aba2000
	v_writelane_b32 v255, s2, 27
	s_addc_u32 s2, s1, 0
	v_writelane_b32 v255, s2, 29
	s_add_u32 s2, s0, 0xbb80000
	v_writelane_b32 v255, s2, 31
	s_addc_u32 s2, s1, 0
	s_add_u32 s20, s0, 0xab40000
	s_addc_u32 s21, s1, 0
	v_lshlrev_b32_e32 v0, 7, v0
	s_add_u32 s22, s0, 0xc7a0000
	v_and_b32_e32 v16, 0x180, v0
	s_addc_u32 s23, s1, 0
	v_lshl_add_u64 v[0:1], s[20:21], 0, v[16:17]
	v_lshlrev_b32_e32 v16, 4, v196
	s_add_u32 s24, s0, 0x1b3c2000
	v_lshl_add_u64 v[200:201], v[0:1], 0, v[16:17]
	v_lshlrev_b32_e32 v0, 3, v2
	v_ashrrev_i32_e32 v199, 31, v198
	s_addc_u32 s25, s1, 0
	v_readlane_b32 s0, v254, 6
	v_writelane_b32 v255, s2, 33
	v_lshlrev_b64 v[202:203], 12, v[198:199]
	v_add_u32_e32 v199, 8, v198
	v_add_u32_e32 v208, 16, v198
	v_add_u32_e32 v209, 24, v198
	v_lshlrev_b32_e32 v204, 1, v0
	s_mov_b32 s48, s0
	v_readfirstlane_b32 s100, v198
	s_lshl_b32 s100, s100, 9
	s_add_i32 s100, s100, 0x20000
	v_readlane_b32 s1, v254, 7
	s_branch .LBB0_2885

; __device__ __forceinline__ void select_group(unsigned char* ws, int r0, const bf16_t* __restrict__ kib, int n, float* sc, SelPre& pre, int nr0, const bf16_t* __restrict__ nkib, int nn) {
;     ...
;       int myc = 0;
; #pragma unroll
;       for (int i = 0; i < 64; ++i) myc += (x[i] >= tau2) ? 1 : 0;
;       int incl = myc;
; #pragma unroll
;       for (int d = 1; d < 64; d <<= 1) {
;         const int t = __shfl_up(incl, d);
;         incl += (lane >= d) ? t : 0;
;       }
.LBB0_3246:
	s_and_b64 vcc, exec, s[0:1]
	s_cbranch_vccz .LBB0_3389
	v_cmp_le_u32_e32 vcc, s8, v238
	v_add_u32_e32 v167, -1, v252
	s_nop 0
	v_cndmask_b32_e64 v16, 0, 1, vcc
	v_cmp_le_u32_e32 vcc, s8, v239
	v_add_u32_e32 v239, -2, v252
	s_nop 0
	v_addc_co_u32_e64 v16, s[0:1], 0, v16, vcc
	v_cmp_le_u32_e64 s[0:1], s8, v237
	s_nop 1
	v_cndmask_b32_e64 v166, 0, 1, s[0:1]
	v_cmp_le_u32_e64 s[0:1], s8, v236
	s_nop 1
	v_addc_co_u32_e64 v16, s[0:1], v16, v166, s[0:1]
	v_cmp_le_u32_e64 s[0:1], s8, v235
	s_nop 1
	v_cndmask_b32_e64 v166, 0, 1, s[0:1]
	v_cmp_le_u32_e64 s[0:1], s8, v234
	s_nop 1
	v_addc_co_u32_e64 v16, s[0:1], v16, v166, s[0:1]
	v_cmp_le_u32_e64 s[0:1], s8, v233
	s_nop 1
	v_cndmask_b32_e64 v166, 0, 1, s[0:1]
	v_cmp_le_u32_e64 s[0:1], s8, v231
	s_nop 1
	v_addc_co_u32_e64 v16, s[0:1], v16, v166, s[0:1]
	v_cmp_le_u32_e64 s[0:1], s8, v232
	s_nop 1
	v_cndmask_b32_e64 v166, 0, 1, s[0:1]
	v_cmp_le_u32_e64 s[0:1], s8, v230
	s_nop 1
	v_addc_co_u32_e64 v16, s[0:1], v16, v166, s[0:1]
	v_cmp_le_u32_e64 s[0:1], s8, v229
	s_nop 1
	v_cndmask_b32_e64 v166, 0, 1, s[0:1]
	v_cmp_le_u32_e64 s[0:1], s8, v228
	s_nop 1
	v_addc_co_u32_e64 v16, s[0:1], v16, v166, s[0:1]
	v_cmp_le_u32_e64 s[0:1], s8, v227
	s_nop 1
	v_cndmask_b32_e64 v166, 0, 1, s[0:1]
	v_cmp_le_u32_e64 s[0:1], s8, v226
	s_nop 1
	v_addc_co_u32_e64 v16, s[0:1], v16, v166, s[0:1]
	v_cmp_le_u32_e64 s[0:1], s8, v225
	s_nop 1
	v_cndmask_b32_e64 v166, 0, 1, s[0:1]
	v_cmp_le_u32_e64 s[0:1], s8, v223
	s_nop 1
	v_addc_co_u32_e64 v16, s[0:1], v16, v166, s[0:1]
	v_cmp_le_u32_e64 s[0:1], s8, v224
	s_nop 1
	v_cndmask_b32_e64 v166, 0, 1, s[0:1]
	v_cmp_le_u32_e64 s[0:1], s8, v222
	s_nop 1
	v_addc_co_u32_e64 v16, s[0:1], v16, v166, s[0:1]
	v_cmp_le_u32_e64 s[0:1], s8, v221
	s_nop 1
	v_cndmask_b32_e64 v166, 0, 1, s[0:1]
	v_cmp_le_u32_e64 s[0:1], s8, v220
	s_nop 1
	v_addc_co_u32_e64 v16, s[0:1], v16, v166, s[0:1]
	v_cmp_le_u32_e64 s[0:1], s8, v219
	s_nop 1
	v_cndmask_b32_e64 v166, 0, 1, s[0:1]
	v_cmp_le_u32_e64 s[0:1], s8, v218
	s_nop 1
	v_addc_co_u32_e64 v16, s[0:1], v16, v166, s[0:1]
	v_cmp_le_u32_e64 s[0:1], s8, v217
	s_nop 1
	v_cndmask_b32_e64 v166, 0, 1, s[0:1]
	v_cmp_le_u32_e64 s[0:1], s8, v215
	s_nop 1
	v_addc_co_u32_e64 v16, s[0:1], v16, v166, s[0:1]
	v_cmp_le_u32_e64 s[0:1], s8, v216
	s_nop 1
	v_cndmask_b32_e64 v166, 0, 1, s[0:1]
	v_cmp_le_u32_e64 s[0:1], s8, v214
	s_nop 1
	v_addc_co_u32_e64 v16, s[0:1], v16, v166, s[0:1]
	v_cmp_le_u32_e64 s[0:1], s8, v213
	s_nop 1
	v_cndmask_b32_e64 v166, 0, 1, s[0:1]
	v_cmp_le_u32_e64 s[0:1], s8, v212
	s_nop 1
	v_addc_co_u32_e64 v16, s[0:1], v16, v166, s[0:1]
	v_cmp_le_u32_e64 s[0:1], s8, v211
	s_nop 1
	v_cndmask_b32_e64 v166, 0, 1, s[0:1]
	v_cmp_le_u32_e64 s[0:1], s8, v210
	s_nop 1
	v_addc_co_u32_e64 v16, s[0:1], v16, v166, s[0:1]
	v_cmp_le_u32_e64 s[0:1], s8, v207
	s_nop 1
	v_cndmask_b32_e64 v166, 0, 1, s[0:1]
	v_cmp_le_u32_e64 s[0:1], s8, v194
	s_nop 1
	v_addc_co_u32_e64 v16, s[0:1], v16, v166, s[0:1]
	v_cmp_le_u32_e64 s[0:1], s8, v195
	s_nop 1
	v_cndmask_b32_e64 v166, 0, 1, s[0:1]
	v_cmp_le_u32_e64 s[0:1], s8, v193
	s_nop 1
	v_addc_co_u32_e64 v16, s[0:1], v16, v166, s[0:1]
	v_cmp_le_u32_e64 s[0:1], s8, v192
	s_nop 1
	v_cndmask_b32_e64 v166, 0, 1, s[0:1]
	v_cmp_le_u32_e64 s[0:1], s8, v191
	s_nop 1
	v_addc_co_u32_e64 v16, s[0:1], v16, v166, s[0:1]
	v_cmp_le_u32_e64 s[0:1], s8, v190
	s_nop 1
	v_cndmask_b32_e64 v166, 0, 1, s[0:1]
	v_cmp_le_u32_e64 s[0:1], s8, v189
	s_nop 1
	v_addc_co_u32_e64 v16, s[0:1], v16, v166, s[0:1]
	v_cmp_le_u32_e64 s[0:1], s8, v188
	s_nop 1
	v_cndmask_b32_e64 v166, 0, 1, s[0:1]
	v_cmp_le_u32_e64 s[0:1], s8, v186
	s_nop 1
	v_addc_co_u32_e64 v16, s[0:1], v16, v166, s[0:1]
	v_cmp_le_u32_e64 s[0:1], s8, v187
	s_nop 1
	v_cndmask_b32_e64 v166, 0, 1, s[0:1]
	v_cmp_le_u32_e64 s[0:1], s8, v185
	s_nop 1
	v_addc_co_u32_e64 v16, s[0:1], v16, v166, s[0:1]
	v_cmp_le_u32_e64 s[0:1], s8, v184
	s_nop 1
	v_cndmask_b32_e64 v166, 0, 1, s[0:1]
	v_cmp_le_u32_e64 s[0:1], s8, v183
	s_nop 1
	v_addc_co_u32_e64 v16, s[0:1], v16, v166, s[0:1]
	v_cmp_le_u32_e64 s[0:1], s8, v182
	s_nop 1
	v_cndmask_b32_e64 v166, 0, 1, s[0:1]
	v_cmp_le_u32_e64 s[0:1], s8, v181
	s_nop 1
	v_addc_co_u32_e64 v16, s[0:1], v16, v166, s[0:1]
	v_cmp_le_u32_e64 s[0:1], s8, v180
	s_nop 1
	v_cndmask_b32_e64 v166, 0, 1, s[0:1]
	v_cmp_le_u32_e64 s[0:1], s8, v178
	s_nop 1
	v_addc_co_u32_e64 v16, s[0:1], v16, v166, s[0:1]
	v_cmp_le_u32_e64 s[0:1], s8, v179
	s_nop 1
	v_cndmask_b32_e64 v166, 0, 1, s[0:1]
	v_cmp_le_u32_e64 s[0:1], s8, v177
	s_nop 1
	v_addc_co_u32_e64 v16, s[0:1], v16, v166, s[0:1]
	v_cmp_le_u32_e64 s[0:1], s8, v176
	s_nop 1
	v_cndmask_b32_e64 v166, 0, 1, s[0:1]
	v_cmp_le_u32_e64 s[0:1], s8, v175
	s_nop 1
	v_addc_co_u32_e64 v16, s[0:1], v16, v166, s[0:1]
	v_cmp_le_u32_e64 s[0:1], s8, v174
	s_nop 1
	v_cndmask_b32_e64 v166, 0, 1, s[0:1]
	v_cmp_le_u32_e64 s[0:1], s8, v173
	s_nop 1
	v_addc_co_u32_e64 v16, s[0:1], v16, v166, s[0:1]
	v_cmp_le_u32_e64 s[0:1], s8, v172
	s_nop 1
	v_cndmask_b32_e64 v166, 0, 1, s[0:1]
	v_cmp_le_u32_e64 s[0:1], s8, v115
	s_nop 1
	v_addc_co_u32_e64 v16, s[0:1], v16, v166, s[0:1]
	v_cmp_le_u32_e64 s[0:1], s8, v243
	s_nop 1
	v_cndmask_b32_e64 v166, 0, 1, s[0:1]
	v_cmp_le_u32_e64 s[0:1], s8, v242
	s_nop 1
	v_addc_co_u32_e64 v16, s[0:1], v16, v166, s[0:1]
	v_cmp_le_u32_e64 s[0:1], s8, v241
	s_nop 1
	v_cndmask_b32_e64 v166, 0, 1, s[0:1]
	v_cmp_le_u32_e64 s[0:1], s8, v240
	s_nop 1
	v_addc_co_u32_e64 v16, s[0:1], v16, v166, s[0:1]
	v_cmp_le_u32_e64 s[0:1], s8, v171
	s_nop 1
	v_cndmask_b32_e64 v166, 0, 1, s[0:1]
	v_cmp_le_u32_e64 s[0:1], s8, v170
	s_nop 1
	v_addc_co_u32_e64 v16, s[0:1], v16, v166, s[0:1]
	v_cmp_le_u32_e64 s[0:1], s8, v169
	s_nop 1
	v_cndmask_b32_e64 v166, 0, 1, s[0:1]
	v_cmp_le_u32_e64 s[0:1], s8, v168
	s_nop 1
	v_addc_co_u32_e64 v16, s[0:1], v16, v166, s[0:1]
	v_and_b32_e32 v166, 64, v252
	v_cmp_lt_i32_e64 s[0:1], v167, v166
	s_nop 1
	v_cndmask_b32_e64 v167, v167, v252, s[0:1]
	v_lshlrev_b32_e32 v167, 2, v167
	ds_bpermute_b32 v167, v167, v16
	v_cmp_ne_u32_e64 s[0:1], 0, v114
	s_waitcnt lgkmcnt(0)
; __device__ __forceinline__ void select_group(unsigned char* ws, int r0, const bf16_t* __restrict__ kib, int n, float* sc, SelPre& pre, int nr0, const bf16_t* __restrict__ nkib, int nn) {
;     ...
;       int incl = myc;
; #pragma unroll
;       for (int d = 1; d < 64; d <<= 1) {
;         const int t = __shfl_up(incl, d);
;         incl += (lane >= d) ? t : 0;
;       }
;       int pos = incl - myc;
; #pragma unroll
;       for (int blk = 0; blk < 8; ++blk) {
;         if (blk * 8 < nreg) {
; #pragma unroll
;           for (int i = blk * 8; i < blk * 8 + 8; ++i) {
;             if (x[i] >= tau2) { selrow[pos] = (unsigned short)(i * 64 + lane); ++pos; }
	s_nop 0
	v_cndmask_b32_e64 v167, 0, v167, s[0:1]
	v_cmp_lt_i32_e64 s[0:1], v239, v166
	v_add_u32_e32 v167, v167, v16
	s_nop 0
	v_cndmask_b32_e64 v239, v239, v252, s[0:1]
	v_lshlrev_b32_e32 v239, 2, v239
	ds_bpermute_b32 v239, v239, v167
	v_cmp_lt_u32_e64 s[0:1], 1, v114
	s_waitcnt lgkmcnt(0)
	s_nop 0
	v_cndmask_b32_e64 v239, 0, v239, s[0:1]
	v_add_u32_e32 v167, v239, v167
	v_add_u32_e32 v239, -4, v252
	v_cmp_lt_i32_e64 s[0:1], v239, v166
	s_nop 1
	v_cndmask_b32_e64 v239, v239, v252, s[0:1]
	v_lshlrev_b32_e32 v239, 2, v239
	ds_bpermute_b32 v239, v239, v167
	v_cmp_lt_u32_e64 s[0:1], 3, v114
	s_waitcnt lgkmcnt(0)
	s_nop 0
	v_cndmask_b32_e64 v239, 0, v239, s[0:1]
	v_add_u32_e32 v167, v239, v167
	v_add_u32_e32 v239, -8, v252
	v_cmp_lt_i32_e64 s[0:1], v239, v166
	s_nop 1
	v_cndmask_b32_e64 v239, v239, v252, s[0:1]
	v_lshlrev_b32_e32 v239, 2, v239
	ds_bpermute_b32 v239, v239, v167
	v_cmp_lt_u32_e64 s[0:1], 7, v114
	s_waitcnt lgkmcnt(0)
	s_nop 0
	v_cndmask_b32_e64 v239, 0, v239, s[0:1]
	v_add_u32_e32 v167, v239, v167
	v_add_u32_e32 v239, -16, v252
	v_cmp_lt_i32_e64 s[0:1], v239, v166
	s_nop 1
	v_cndmask_b32_e64 v239, v239, v252, s[0:1]
	v_lshlrev_b32_e32 v239, 2, v239
	ds_bpermute_b32 v239, v239, v167
	v_cmp_lt_u32_e64 s[0:1], 15, v114
	s_waitcnt lgkmcnt(0)
	s_nop 0
	v_cndmask_b32_e64 v239, 0, v239, s[0:1]
	v_add_u32_e32 v167, v239, v167
	v_subrev_u32_e32 v239, 32, v252
	v_cmp_lt_i32_e64 s[0:1], v239, v166
	v_sub_u32_e32 v16, v167, v16
	s_nop 0
	v_cndmask_b32_e64 v166, v239, v252, s[0:1]
	v_lshlrev_b32_e32 v166, 2, v166
	ds_bpermute_b32 v166, v166, v167
	v_cmp_lt_u32_e64 s[0:1], 31, v114
	s_waitcnt lgkmcnt(0)
	s_nop 0
	v_cndmask_b32_e64 v166, 0, v166, s[0:1]
	v_add_u32_e32 v166, v16, v166
	s_and_saveexec_b64 s[0:1], vcc
	s_cbranch_execz .LBB0_3264
	v_add_u32_e32 v16, 1, v166
	v_lshl_add_u32 v167, v166, 1, s100
	ds_write_b16 v167, v114
	v_mov_b32_e32 v166, v16
	s_or_b64 exec, exec, s[0:1]
	v_cmp_le_u32_e32 vcc, s8, v238
	s_and_saveexec_b64 s[0:1], vcc
	s_cbranch_execnz .LBB0_3265

; __device__ __forceinline__ void select_group(unsigned char* ws, int r0, const bf16_t* __restrict__ kib, int n, float* sc, SelPre& pre, int nr0, const bf16_t* __restrict__ nkib, int nn) {
;     ...
;       for (int blk = 0; blk < 8; ++blk) {
;         if (blk * 8 < nreg) {
; #pragma unroll
;           for (int i = blk * 8; i < blk * 8 + 8; ++i) {
;             if (x[i] >= tau2) { selrow[pos] = (unsigned short)(i * 64 + lane); ++pos; }
;           }
;         }
.LBB0_3250:
	v_add_u32_e32 v16, 1, v166
	v_lshl_add_u32 v167, v166, 1, s100
	v_or_b32_e32 v237, 0x80, v114
	ds_write_b16 v167, v237
	v_mov_b32_e32 v166, v16
	s_or_b64 exec, exec, s[0:1]
	v_cmp_le_u32_e32 vcc, s8, v236
	s_and_saveexec_b64 s[0:1], vcc
	s_cbranch_execnz .LBB0_3267

; __device__ __forceinline__ void select_group(unsigned char* ws, int r0, const bf16_t* __restrict__ kib, int n, float* sc, SelPre& pre, int nr0, const bf16_t* __restrict__ nkib, int nn) {
;     ...
;       for (int blk = 0; blk < 8; ++blk) {
;         if (blk * 8 < nreg) {
; #pragma unroll
;           for (int i = blk * 8; i < blk * 8 + 8; ++i) {
;             if (x[i] >= tau2) { selrow[pos] = (unsigned short)(i * 64 + lane); ++pos; }
;           }
;         }
.LBB0_3252:
	v_add_u32_e32 v16, 1, v166
	v_lshl_add_u32 v167, v166, 1, s100
	v_or_b32_e32 v235, 0x100, v114
	ds_write_b16 v167, v235
	v_mov_b32_e32 v166, v16
	s_or_b64 exec, exec, s[0:1]
	v_cmp_le_u32_e32 vcc, s8, v234
	s_and_saveexec_b64 s[0:1], vcc
	s_cbranch_execnz .LBB0_3269

; __device__ __forceinline__ void select_group(unsigned char* ws, int r0, const bf16_t* __restrict__ kib, int n, float* sc, SelPre& pre, int nr0, const bf16_t* __restrict__ nkib, int nn) {
;     ...
;       for (int blk = 0; blk < 8; ++blk) {
;         if (blk * 8 < nreg) {
; #pragma unroll
;           for (int i = blk * 8; i < blk * 8 + 8; ++i) {
;             if (x[i] >= tau2) { selrow[pos] = (unsigned short)(i * 64 + lane); ++pos; }
;           }
;         }
.LBB0_3254:
	v_add_u32_e32 v16, 1, v166
	v_lshl_add_u32 v167, v166, 1, s100
	v_or_b32_e32 v233, 0x180, v114
	ds_write_b16 v167, v233
	v_mov_b32_e32 v166, v16
	s_or_b64 exec, exec, s[0:1]
	v_cmp_le_u32_e32 vcc, s8, v231
	s_and_saveexec_b64 s[0:1], vcc
	s_cbranch_execnz .LBB0_3271

; __device__ __forceinline__ void select_group(unsigned char* ws, int r0, const bf16_t* __restrict__ kib, int n, float* sc, SelPre& pre, int nr0, const bf16_t* __restrict__ nkib, int nn) {
;     ...
;       for (int blk = 0; blk < 8; ++blk) {
;         if (blk * 8 < nreg) {
; #pragma unroll
;           for (int i = blk * 8; i < blk * 8 + 8; ++i) {
;             if (x[i] >= tau2) { selrow[pos] = (unsigned short)(i * 64 + lane); ++pos; }
;           }
;         }
.LBB0_3256:
	v_cmp_le_u32_e32 vcc, s8, v232
	s_and_saveexec_b64 s[0:1], vcc
	s_cbranch_execz .LBB0_3281
	v_add_u32_e32 v16, 1, v166
	v_lshl_add_u32 v167, v166, 1, s100
	v_or_b32_e32 v231, 0x200, v114
	ds_write_b16 v167, v231
	v_mov_b32_e32 v166, v16
	s_or_b64 exec, exec, s[0:1]
	v_cmp_le_u32_e32 vcc, s8, v230
	s_and_saveexec_b64 s[0:1], vcc
	s_cbranch_execnz .LBB0_3282

; __device__ __forceinline__ void select_group(unsigned char* ws, int r0, const bf16_t* __restrict__ kib, int n, float* sc, SelPre& pre, int nr0, const bf16_t* __restrict__ nkib, int nn) {
;     ...
;       for (int blk = 0; blk < 8; ++blk) {
;         if (blk * 8 < nreg) {
; #pragma unroll
;           for (int i = blk * 8; i < blk * 8 + 8; ++i) {
;             if (x[i] >= tau2) { selrow[pos] = (unsigned short)(i * 64 + lane); ++pos; }
;           }
;         }
.LBB0_3259:
	v_add_u32_e32 v16, 1, v166
	v_lshl_add_u32 v167, v166, 1, s100
	v_or_b32_e32 v229, 0x280, v114
	ds_write_b16 v167, v229
	v_mov_b32_e32 v166, v16
	s_or_b64 exec, exec, s[0:1]
	v_cmp_le_u32_e32 vcc, s8, v228
	s_and_saveexec_b64 s[0:1], vcc
	s_cbranch_execnz .LBB0_3284

; __device__ __forceinline__ void select_group(unsigned char* ws, int r0, const bf16_t* __restrict__ kib, int n, float* sc, SelPre& pre, int nr0, const bf16_t* __restrict__ nkib, int nn) {
;     ...
;       for (int blk = 0; blk < 8; ++blk) {
;         if (blk * 8 < nreg) {
; #pragma unroll
;           for (int i = blk * 8; i < blk * 8 + 8; ++i) {
;             if (x[i] >= tau2) { selrow[pos] = (unsigned short)(i * 64 + lane); ++pos; }
;           }
;         }
.LBB0_3261:
	v_add_u32_e32 v16, 1, v166
	v_lshl_add_u32 v167, v166, 1, s100
	v_or_b32_e32 v227, 0x300, v114
	ds_write_b16 v167, v227
	v_mov_b32_e32 v166, v16
	s_or_b64 exec, exec, s[0:1]
	v_cmp_le_u32_e32 vcc, s8, v226
	s_and_saveexec_b64 s[0:1], vcc
	s_cbranch_execnz .LBB0_3286

; __device__ __forceinline__ void select_group(unsigned char* ws, int r0, const bf16_t* __restrict__ kib, int n, float* sc, SelPre& pre, int nr0, const bf16_t* __restrict__ nkib, int nn) {
;     ...
;       for (int blk = 0; blk < 8; ++blk) {
;         if (blk * 8 < nreg) {
; #pragma unroll
;           for (int i = blk * 8; i < blk * 8 + 8; ++i) {
;             if (x[i] >= tau2) { selrow[pos] = (unsigned short)(i * 64 + lane); ++pos; }
;           }
;         }
.LBB0_3263:
	v_add_u32_e32 v16, 1, v166
	v_lshl_add_u32 v167, v166, 1, s100
	v_or_b32_e32 v225, 0x380, v114
	ds_write_b16 v167, v225
	v_mov_b32_e32 v166, v16
	s_or_b64 exec, exec, s[0:1]
	v_cmp_le_u32_e32 vcc, s8, v223
	s_and_saveexec_b64 s[0:1], vcc
	s_cbranch_execnz .LBB0_3288
	s_branch .LBB0_3289

; __device__ __forceinline__ void select_group(unsigned char* ws, int r0, const bf16_t* __restrict__ kib, int n, float* sc, SelPre& pre, int nr0, const bf16_t* __restrict__ nkib, int nn) {
;     ...
;       for (int blk = 0; blk < 8; ++blk) {
;         if (blk * 8 < nreg) {
; #pragma unroll
;           for (int i = blk * 8; i < blk * 8 + 8; ++i) {
;             if (x[i] >= tau2) { selrow[pos] = (unsigned short)(i * 64 + lane); ++pos; }
;           }
;         }
.LBB0_3265:
	v_add_u32_e32 v16, 1, v166
	v_lshl_add_u32 v167, v166, 1, s100
	v_or_b32_e32 v238, 64, v114
	ds_write_b16 v167, v238
	v_mov_b32_e32 v166, v16
	s_or_b64 exec, exec, s[0:1]
	v_cmp_le_u32_e32 vcc, s8, v237
	s_and_saveexec_b64 s[0:1], vcc
	s_cbranch_execnz .LBB0_3250

; __device__ __forceinline__ void select_group(unsigned char* ws, int r0, const bf16_t* __restrict__ kib, int n, float* sc, SelPre& pre, int nr0, const bf16_t* __restrict__ nkib, int nn) {
;     ...
;       for (int blk = 0; blk < 8; ++blk) {
;         if (blk * 8 < nreg) {
; #pragma unroll
;           for (int i = blk * 8; i < blk * 8 + 8; ++i) {
;             if (x[i] >= tau2) { selrow[pos] = (unsigned short)(i * 64 + lane); ++pos; }
;           }
;         }
.LBB0_3267:
	v_add_u32_e32 v16, 1, v166
	v_lshl_add_u32 v167, v166, 1, s100
	v_or_b32_e32 v236, 0xc0, v114
	ds_write_b16 v167, v236
	v_mov_b32_e32 v166, v16
	s_or_b64 exec, exec, s[0:1]
	v_cmp_le_u32_e32 vcc, s8, v235
	s_and_saveexec_b64 s[0:1], vcc
	s_cbranch_execnz .LBB0_3252

; __device__ __forceinline__ void select_group(unsigned char* ws, int r0, const bf16_t* __restrict__ kib, int n, float* sc, SelPre& pre, int nr0, const bf16_t* __restrict__ nkib, int nn) {
;     ...
;       for (int blk = 0; blk < 8; ++blk) {
;         if (blk * 8 < nreg) {
; #pragma unroll
;           for (int i = blk * 8; i < blk * 8 + 8; ++i) {
;             if (x[i] >= tau2) { selrow[pos] = (unsigned short)(i * 64 + lane); ++pos; }
;           }
;         }
.LBB0_3269:
	v_add_u32_e32 v16, 1, v166
	v_lshl_add_u32 v167, v166, 1, s100
	v_or_b32_e32 v234, 0x140, v114
	ds_write_b16 v167, v234
	v_mov_b32_e32 v166, v16
	s_or_b64 exec, exec, s[0:1]
	v_cmp_le_u32_e32 vcc, s8, v233
	s_and_saveexec_b64 s[0:1], vcc
	s_cbranch_execnz .LBB0_3254

; __device__ __forceinline__ void select_group(unsigned char* ws, int r0, const bf16_t* __restrict__ kib, int n, float* sc, SelPre& pre, int nr0, const bf16_t* __restrict__ nkib, int nn) {
;     ...
;       for (int blk = 0; blk < 8; ++blk) {
;         if (blk * 8 < nreg) {
; #pragma unroll
;           for (int i = blk * 8; i < blk * 8 + 8; ++i) {
;             if (x[i] >= tau2) { selrow[pos] = (unsigned short)(i * 64 + lane); ++pos; }
;           }
;         }
.LBB0_3271:
	v_add_u32_e32 v16, 1, v166
	v_lshl_add_u32 v167, v166, 1, s100
	v_or_b32_e32 v231, 0x1c0, v114
	ds_write_b16 v167, v231
	v_mov_b32_e32 v166, v16
	s_or_b64 exec, exec, s[0:1]
	s_cmpk_lt_u32 s57, 0x201
	s_cbranch_scc0 .LBB0_3256

; __device__ __forceinline__ void select_group(unsigned char* ws, int r0, const bf16_t* __restrict__ kib, int n, float* sc, SelPre& pre, int nr0, const bf16_t* __restrict__ nkib, int nn) {
;     ...
;       for (int blk = 0; blk < 8; ++blk) {
;         if (blk * 8 < nreg) {
; #pragma unroll
;           for (int i = blk * 8; i < blk * 8 + 8; ++i) {
;             if (x[i] >= tau2) { selrow[pos] = (unsigned short)(i * 64 + lane); ++pos; }
;           }
;         }
.LBB0_3273:
	v_cmp_le_u32_e32 vcc, s8, v224
	s_and_saveexec_b64 s[0:1], vcc
	s_cbranch_execz .LBB0_3299
	v_add_u32_e32 v16, 1, v166
	v_lshl_add_u32 v167, v166, 1, s100
	v_or_b32_e32 v223, 0x400, v114
	ds_write_b16 v167, v223
	v_mov_b32_e32 v166, v16
	s_or_b64 exec, exec, s[0:1]
	v_cmp_le_u32_e32 vcc, s8, v222
	s_and_saveexec_b64 s[0:1], vcc
	s_cbranch_execnz .LBB0_3300

; __device__ __forceinline__ void select_group(unsigned char* ws, int r0, const bf16_t* __restrict__ kib, int n, float* sc, SelPre& pre, int nr0, const bf16_t* __restrict__ nkib, int nn) {
;     ...
;       for (int blk = 0; blk < 8; ++blk) {
;         if (blk * 8 < nreg) {
; #pragma unroll
;           for (int i = blk * 8; i < blk * 8 + 8; ++i) {
;             if (x[i] >= tau2) { selrow[pos] = (unsigned short)(i * 64 + lane); ++pos; }
;           }
;         }
.LBB0_3276:
	v_add_u32_e32 v16, 1, v166
	v_lshl_add_u32 v167, v166, 1, s100
	v_or_b32_e32 v221, 0x480, v114
	ds_write_b16 v167, v221
	v_mov_b32_e32 v166, v16
	s_or_b64 exec, exec, s[0:1]
	v_cmp_le_u32_e32 vcc, s8, v220
	s_and_saveexec_b64 s[0:1], vcc
	s_cbranch_execnz .LBB0_3302

; __device__ __forceinline__ void select_group(unsigned char* ws, int r0, const bf16_t* __restrict__ kib, int n, float* sc, SelPre& pre, int nr0, const bf16_t* __restrict__ nkib, int nn) {
;     ...
;       for (int blk = 0; blk < 8; ++blk) {
;         if (blk * 8 < nreg) {
; #pragma unroll
;           for (int i = blk * 8; i < blk * 8 + 8; ++i) {
;             if (x[i] >= tau2) { selrow[pos] = (unsigned short)(i * 64 + lane); ++pos; }
;           }
;         }
.LBB0_3278:
	v_add_u32_e32 v16, 1, v166
	v_lshl_add_u32 v167, v166, 1, s100
	v_or_b32_e32 v219, 0x500, v114
	ds_write_b16 v167, v219
	v_mov_b32_e32 v166, v16
	s_or_b64 exec, exec, s[0:1]
	v_cmp_le_u32_e32 vcc, s8, v218
	s_and_saveexec_b64 s[0:1], vcc
	s_cbranch_execnz .LBB0_3304

; __device__ __forceinline__ void select_group(unsigned char* ws, int r0, const bf16_t* __restrict__ kib, int n, float* sc, SelPre& pre, int nr0, const bf16_t* __restrict__ nkib, int nn) {
;     ...
;       for (int blk = 0; blk < 8; ++blk) {
;         if (blk * 8 < nreg) {
; #pragma unroll
;           for (int i = blk * 8; i < blk * 8 + 8; ++i) {
;             if (x[i] >= tau2) { selrow[pos] = (unsigned short)(i * 64 + lane); ++pos; }
;           }
;         }
.LBB0_3280:
	v_add_u32_e32 v16, 1, v166
	v_lshl_add_u32 v167, v166, 1, s100
	v_or_b32_e32 v217, 0x580, v114
	ds_write_b16 v167, v217
	v_mov_b32_e32 v166, v16
	s_or_b64 exec, exec, s[0:1]
	v_cmp_le_u32_e32 vcc, s8, v215
	s_and_saveexec_b64 s[0:1], vcc
	s_cbranch_execnz .LBB0_3306
	s_branch .LBB0_3307

; __device__ __forceinline__ void select_group(unsigned char* ws, int r0, const bf16_t* __restrict__ kib, int n, float* sc, SelPre& pre, int nr0, const bf16_t* __restrict__ nkib, int nn) {
;     ...
;       for (int blk = 0; blk < 8; ++blk) {
;         if (blk * 8 < nreg) {
; #pragma unroll
;           for (int i = blk * 8; i < blk * 8 + 8; ++i) {
;             if (x[i] >= tau2) { selrow[pos] = (unsigned short)(i * 64 + lane); ++pos; }
;           }
;         }
.LBB0_3282:
	v_add_u32_e32 v16, 1, v166
	v_lshl_add_u32 v167, v166, 1, s100
	v_or_b32_e32 v230, 0x240, v114
	ds_write_b16 v167, v230
	v_mov_b32_e32 v166, v16
	s_or_b64 exec, exec, s[0:1]
	v_cmp_le_u32_e32 vcc, s8, v229
	s_and_saveexec_b64 s[0:1], vcc
	s_cbranch_execnz .LBB0_3259

; __device__ __forceinline__ void select_group(unsigned char* ws, int r0, const bf16_t* __restrict__ kib, int n, float* sc, SelPre& pre, int nr0, const bf16_t* __restrict__ nkib, int nn) {
;     ...
;       for (int blk = 0; blk < 8; ++blk) {
;         if (blk * 8 < nreg) {
; #pragma unroll
;           for (int i = blk * 8; i < blk * 8 + 8; ++i) {
;             if (x[i] >= tau2) { selrow[pos] = (unsigned short)(i * 64 + lane); ++pos; }
;           }
;         }
.LBB0_3284:
	v_add_u32_e32 v16, 1, v166
	v_lshl_add_u32 v167, v166, 1, s100
	v_or_b32_e32 v228, 0x2c0, v114
	ds_write_b16 v167, v228
	v_mov_b32_e32 v166, v16
	s_or_b64 exec, exec, s[0:1]
	v_cmp_le_u32_e32 vcc, s8, v227
	s_and_saveexec_b64 s[0:1], vcc
	s_cbranch_execnz .LBB0_3261

; __device__ __forceinline__ void select_group(unsigned char* ws, int r0, const bf16_t* __restrict__ kib, int n, float* sc, SelPre& pre, int nr0, const bf16_t* __restrict__ nkib, int nn) {
;     ...
;       for (int blk = 0; blk < 8; ++blk) {
;         if (blk * 8 < nreg) {
; #pragma unroll
;           for (int i = blk * 8; i < blk * 8 + 8; ++i) {
;             if (x[i] >= tau2) { selrow[pos] = (unsigned short)(i * 64 + lane); ++pos; }
;           }
;         }
.LBB0_3286:
	v_add_u32_e32 v16, 1, v166
	v_lshl_add_u32 v167, v166, 1, s100
	v_or_b32_e32 v226, 0x340, v114
	ds_write_b16 v167, v226
	v_mov_b32_e32 v166, v16
	s_or_b64 exec, exec, s[0:1]
	v_cmp_le_u32_e32 vcc, s8, v225
	s_and_saveexec_b64 s[0:1], vcc
	s_cbranch_execnz .LBB0_3263

; __device__ __forceinline__ void select_group(unsigned char* ws, int r0, const bf16_t* __restrict__ kib, int n, float* sc, SelPre& pre, int nr0, const bf16_t* __restrict__ nkib, int nn) {
;     ...
;       for (int blk = 0; blk < 8; ++blk) {
;         if (blk * 8 < nreg) {
; #pragma unroll
;           for (int i = blk * 8; i < blk * 8 + 8; ++i) {
;             if (x[i] >= tau2) { selrow[pos] = (unsigned short)(i * 64 + lane); ++pos; }
;           }
;         }
.LBB0_3288:
	v_add_u32_e32 v16, 1, v166
	v_lshl_add_u32 v167, v166, 1, s100
	v_or_b32_e32 v223, 0x3c0, v114
	ds_write_b16 v167, v223
	v_mov_b32_e32 v166, v16

; __device__ __forceinline__ void select_group(unsigned char* ws, int r0, const bf16_t* __restrict__ kib, int n, float* sc, SelPre& pre, int nr0, const bf16_t* __restrict__ nkib, int nn) {
;     ...
;       for (int blk = 0; blk < 8; ++blk) {
;         if (blk * 8 < nreg) {
; #pragma unroll
;           for (int i = blk * 8; i < blk * 8 + 8; ++i) {
;             if (x[i] >= tau2) { selrow[pos] = (unsigned short)(i * 64 + lane); ++pos; }
;           }
;         }
.LBB0_3291:
	v_cmp_le_u32_e32 vcc, s8, v216
	s_and_saveexec_b64 s[0:1], vcc
	s_cbranch_execz .LBB0_3317
	v_add_u32_e32 v16, 1, v166
	v_lshl_add_u32 v167, v166, 1, s100
	v_or_b32_e32 v215, 0x600, v114
	ds_write_b16 v167, v215
	v_mov_b32_e32 v166, v16
	s_or_b64 exec, exec, s[0:1]
	v_cmp_le_u32_e32 vcc, s8, v214
	s_and_saveexec_b64 s[0:1], vcc
	s_cbranch_execnz .LBB0_3318

; __device__ __forceinline__ void select_group(unsigned char* ws, int r0, const bf16_t* __restrict__ kib, int n, float* sc, SelPre& pre, int nr0, const bf16_t* __restrict__ nkib, int nn) {
;     ...
;       for (int blk = 0; blk < 8; ++blk) {
;         if (blk * 8 < nreg) {
; #pragma unroll
;           for (int i = blk * 8; i < blk * 8 + 8; ++i) {
;             if (x[i] >= tau2) { selrow[pos] = (unsigned short)(i * 64 + lane); ++pos; }
;           }
;         }
.LBB0_3294:
	v_add_u32_e32 v16, 1, v166
	v_lshl_add_u32 v167, v166, 1, s100
	v_or_b32_e32 v213, 0x680, v114
	ds_write_b16 v167, v213
	v_mov_b32_e32 v166, v16
	s_or_b64 exec, exec, s[0:1]
	v_cmp_le_u32_e32 vcc, s8, v212
	s_and_saveexec_b64 s[0:1], vcc
	s_cbranch_execnz .LBB0_3320

; __device__ __forceinline__ void select_group(unsigned char* ws, int r0, const bf16_t* __restrict__ kib, int n, float* sc, SelPre& pre, int nr0, const bf16_t* __restrict__ nkib, int nn) {
;     ...
;       for (int blk = 0; blk < 8; ++blk) {
;         if (blk * 8 < nreg) {
; #pragma unroll
;           for (int i = blk * 8; i < blk * 8 + 8; ++i) {
;             if (x[i] >= tau2) { selrow[pos] = (unsigned short)(i * 64 + lane); ++pos; }
;           }
;         }
.LBB0_3296:
	v_add_u32_e32 v16, 1, v166
	v_lshl_add_u32 v167, v166, 1, s100
	v_or_b32_e32 v211, 0x700, v114
	ds_write_b16 v167, v211
	v_mov_b32_e32 v166, v16
	s_or_b64 exec, exec, s[0:1]
	v_cmp_le_u32_e32 vcc, s8, v210
	s_and_saveexec_b64 s[0:1], vcc
	s_cbranch_execnz .LBB0_3322

; __device__ __forceinline__ void select_group(unsigned char* ws, int r0, const bf16_t* __restrict__ kib, int n, float* sc, SelPre& pre, int nr0, const bf16_t* __restrict__ nkib, int nn) {
;     ...
;       for (int blk = 0; blk < 8; ++blk) {
;         if (blk * 8 < nreg) {
; #pragma unroll
;           for (int i = blk * 8; i < blk * 8 + 8; ++i) {
;             if (x[i] >= tau2) { selrow[pos] = (unsigned short)(i * 64 + lane); ++pos; }
;           }
;         }
.LBB0_3298:
	v_add_u32_e32 v16, 1, v166
	v_lshl_add_u32 v167, v166, 1, s100
	v_or_b32_e32 v207, 0x780, v114
	ds_write_b16 v167, v207
	v_mov_b32_e32 v166, v16
	s_or_b64 exec, exec, s[0:1]
	v_cmp_le_u32_e32 vcc, s8, v194
	s_and_saveexec_b64 s[0:1], vcc
	s_cbranch_execnz .LBB0_3324
	s_branch .LBB0_3325

; __device__ __forceinline__ void select_group(unsigned char* ws, int r0, const bf16_t* __restrict__ kib, int n, float* sc, SelPre& pre, int nr0, const bf16_t* __restrict__ nkib, int nn) {
;     ...
;       for (int blk = 0; blk < 8; ++blk) {
;         if (blk * 8 < nreg) {
; #pragma unroll
;           for (int i = blk * 8; i < blk * 8 + 8; ++i) {
;             if (x[i] >= tau2) { selrow[pos] = (unsigned short)(i * 64 + lane); ++pos; }
;           }
;         }
.LBB0_3300:
	v_add_u32_e32 v16, 1, v166
	v_lshl_add_u32 v167, v166, 1, s100
	v_or_b32_e32 v222, 0x440, v114
	ds_write_b16 v167, v222
	v_mov_b32_e32 v166, v16
	s_or_b64 exec, exec, s[0:1]
	v_cmp_le_u32_e32 vcc, s8, v221
	s_and_saveexec_b64 s[0:1], vcc
	s_cbranch_execnz .LBB0_3276

; __device__ __forceinline__ void select_group(unsigned char* ws, int r0, const bf16_t* __restrict__ kib, int n, float* sc, SelPre& pre, int nr0, const bf16_t* __restrict__ nkib, int nn) {
;     ...
;       for (int blk = 0; blk < 8; ++blk) {
;         if (blk * 8 < nreg) {
; #pragma unroll
;           for (int i = blk * 8; i < blk * 8 + 8; ++i) {
;             if (x[i] >= tau2) { selrow[pos] = (unsigned short)(i * 64 + lane); ++pos; }
;           }
;         }
.LBB0_3302:
	v_add_u32_e32 v16, 1, v166
	v_lshl_add_u32 v167, v166, 1, s100
	v_or_b32_e32 v220, 0x4c0, v114
	ds_write_b16 v167, v220
	v_mov_b32_e32 v166, v16
	s_or_b64 exec, exec, s[0:1]
	v_cmp_le_u32_e32 vcc, s8, v219
	s_and_saveexec_b64 s[0:1], vcc
	s_cbranch_execnz .LBB0_3278

; __device__ __forceinline__ void select_group(unsigned char* ws, int r0, const bf16_t* __restrict__ kib, int n, float* sc, SelPre& pre, int nr0, const bf16_t* __restrict__ nkib, int nn) {
;     ...
;       for (int blk = 0; blk < 8; ++blk) {
;         if (blk * 8 < nreg) {
; #pragma unroll
;           for (int i = blk * 8; i < blk * 8 + 8; ++i) {
;             if (x[i] >= tau2) { selrow[pos] = (unsigned short)(i * 64 + lane); ++pos; }
;           }
;         }
.LBB0_3304:
	v_add_u32_e32 v16, 1, v166
	v_lshl_add_u32 v167, v166, 1, s100
	v_or_b32_e32 v218, 0x540, v114
	ds_write_b16 v167, v218
	v_mov_b32_e32 v166, v16
	s_or_b64 exec, exec, s[0:1]
	v_cmp_le_u32_e32 vcc, s8, v217
	s_and_saveexec_b64 s[0:1], vcc
	s_cbranch_execnz .LBB0_3280

; __device__ __forceinline__ void select_group(unsigned char* ws, int r0, const bf16_t* __restrict__ kib, int n, float* sc, SelPre& pre, int nr0, const bf16_t* __restrict__ nkib, int nn) {
;     ...
;       for (int blk = 0; blk < 8; ++blk) {
;         if (blk * 8 < nreg) {
; #pragma unroll
;           for (int i = blk * 8; i < blk * 8 + 8; ++i) {
;             if (x[i] >= tau2) { selrow[pos] = (unsigned short)(i * 64 + lane); ++pos; }
;           }
;         }
.LBB0_3306:
	v_add_u32_e32 v16, 1, v166
	v_lshl_add_u32 v167, v166, 1, s100
	v_or_b32_e32 v215, 0x5c0, v114
	ds_write_b16 v167, v215
	v_mov_b32_e32 v166, v16

; __device__ __forceinline__ void select_group(unsigned char* ws, int r0, const bf16_t* __restrict__ kib, int n, float* sc, SelPre& pre, int nr0, const bf16_t* __restrict__ nkib, int nn) {
;     ...
;       for (int blk = 0; blk < 8; ++blk) {
;         if (blk * 8 < nreg) {
; #pragma unroll
;           for (int i = blk * 8; i < blk * 8 + 8; ++i) {
;             if (x[i] >= tau2) { selrow[pos] = (unsigned short)(i * 64 + lane); ++pos; }
;           }
;         }
.LBB0_3309:
	v_cmp_le_u32_e32 vcc, s8, v195
	s_and_saveexec_b64 s[0:1], vcc
	s_cbranch_execz .LBB0_3335
	v_add_u32_e32 v16, 1, v166
	v_lshl_add_u32 v167, v166, 1, s100
	v_or_b32_e32 v194, 0x800, v114
	ds_write_b16 v167, v194
	v_mov_b32_e32 v166, v16
	s_or_b64 exec, exec, s[0:1]
	v_cmp_le_u32_e32 vcc, s8, v193
	s_and_saveexec_b64 s[0:1], vcc
	s_cbranch_execnz .LBB0_3336

; __device__ __forceinline__ void select_group(unsigned char* ws, int r0, const bf16_t* __restrict__ kib, int n, float* sc, SelPre& pre, int nr0, const bf16_t* __restrict__ nkib, int nn) {
;     ...
;       for (int blk = 0; blk < 8; ++blk) {
;         if (blk * 8 < nreg) {
; #pragma unroll
;           for (int i = blk * 8; i < blk * 8 + 8; ++i) {
;             if (x[i] >= tau2) { selrow[pos] = (unsigned short)(i * 64 + lane); ++pos; }
;           }
;         }
.LBB0_3312:
	v_add_u32_e32 v16, 1, v166
	v_lshl_add_u32 v167, v166, 1, s100
	v_or_b32_e32 v192, 0x880, v114
	ds_write_b16 v167, v192
	v_mov_b32_e32 v166, v16
	s_or_b64 exec, exec, s[0:1]
	v_cmp_le_u32_e32 vcc, s8, v191
	s_and_saveexec_b64 s[0:1], vcc
	s_cbranch_execnz .LBB0_3338

; __device__ __forceinline__ void select_group(unsigned char* ws, int r0, const bf16_t* __restrict__ kib, int n, float* sc, SelPre& pre, int nr0, const bf16_t* __restrict__ nkib, int nn) {
;     ...
;       for (int blk = 0; blk < 8; ++blk) {
;         if (blk * 8 < nreg) {
; #pragma unroll
;           for (int i = blk * 8; i < blk * 8 + 8; ++i) {
;             if (x[i] >= tau2) { selrow[pos] = (unsigned short)(i * 64 + lane); ++pos; }
;           }
;         }
.LBB0_3314:
	v_add_u32_e32 v16, 1, v166
	v_lshl_add_u32 v167, v166, 1, s100
	v_or_b32_e32 v190, 0x900, v114
	ds_write_b16 v167, v190
	v_mov_b32_e32 v166, v16
	s_or_b64 exec, exec, s[0:1]
	v_cmp_le_u32_e32 vcc, s8, v189
	s_and_saveexec_b64 s[0:1], vcc
	s_cbranch_execnz .LBB0_3340

; __device__ __forceinline__ void select_group(unsigned char* ws, int r0, const bf16_t* __restrict__ kib, int n, float* sc, SelPre& pre, int nr0, const bf16_t* __restrict__ nkib, int nn) {
;     ...
;       for (int blk = 0; blk < 8; ++blk) {
;         if (blk * 8 < nreg) {
; #pragma unroll
;           for (int i = blk * 8; i < blk * 8 + 8; ++i) {
;             if (x[i] >= tau2) { selrow[pos] = (unsigned short)(i * 64 + lane); ++pos; }
;           }
;         }
.LBB0_3316:
	v_add_u32_e32 v16, 1, v166
	v_lshl_add_u32 v167, v166, 1, s100
	v_or_b32_e32 v188, 0x980, v114
	ds_write_b16 v167, v188
	v_mov_b32_e32 v166, v16
	s_or_b64 exec, exec, s[0:1]
	v_cmp_le_u32_e32 vcc, s8, v186
	s_and_saveexec_b64 s[0:1], vcc
	s_cbranch_execnz .LBB0_3342
	s_branch .LBB0_3343

; __device__ __forceinline__ void select_group(unsigned char* ws, int r0, const bf16_t* __restrict__ kib, int n, float* sc, SelPre& pre, int nr0, const bf16_t* __restrict__ nkib, int nn) {
;     ...
;       for (int blk = 0; blk < 8; ++blk) {
;         if (blk * 8 < nreg) {
; #pragma unroll
;           for (int i = blk * 8; i < blk * 8 + 8; ++i) {
;             if (x[i] >= tau2) { selrow[pos] = (unsigned short)(i * 64 + lane); ++pos; }
;           }
;         }
.LBB0_3318:
	v_add_u32_e32 v16, 1, v166
	v_lshl_add_u32 v167, v166, 1, s100
	v_or_b32_e32 v214, 0x640, v114
	ds_write_b16 v167, v214
	v_mov_b32_e32 v166, v16
	s_or_b64 exec, exec, s[0:1]
	v_cmp_le_u32_e32 vcc, s8, v213
	s_and_saveexec_b64 s[0:1], vcc
	s_cbranch_execnz .LBB0_3294

; __device__ __forceinline__ void select_group(unsigned char* ws, int r0, const bf16_t* __restrict__ kib, int n, float* sc, SelPre& pre, int nr0, const bf16_t* __restrict__ nkib, int nn) {
;     ...
;       for (int blk = 0; blk < 8; ++blk) {
;         if (blk * 8 < nreg) {
; #pragma unroll
;           for (int i = blk * 8; i < blk * 8 + 8; ++i) {
;             if (x[i] >= tau2) { selrow[pos] = (unsigned short)(i * 64 + lane); ++pos; }
;           }
;         }
.LBB0_3320:
	v_add_u32_e32 v16, 1, v166
	v_lshl_add_u32 v167, v166, 1, s100
	v_or_b32_e32 v212, 0x6c0, v114
	ds_write_b16 v167, v212
	v_mov_b32_e32 v166, v16
	s_or_b64 exec, exec, s[0:1]
	v_cmp_le_u32_e32 vcc, s8, v211
	s_and_saveexec_b64 s[0:1], vcc
	s_cbranch_execnz .LBB0_3296

; __device__ __forceinline__ void select_group(unsigned char* ws, int r0, const bf16_t* __restrict__ kib, int n, float* sc, SelPre& pre, int nr0, const bf16_t* __restrict__ nkib, int nn) {
;     ...
;       for (int blk = 0; blk < 8; ++blk) {
;         if (blk * 8 < nreg) {
; #pragma unroll
;           for (int i = blk * 8; i < blk * 8 + 8; ++i) {
;             if (x[i] >= tau2) { selrow[pos] = (unsigned short)(i * 64 + lane); ++pos; }
;           }
;         }
.LBB0_3322:
	v_add_u32_e32 v16, 1, v166
	v_lshl_add_u32 v167, v166, 1, s100
	v_or_b32_e32 v210, 0x740, v114
	ds_write_b16 v167, v210
	v_mov_b32_e32 v166, v16
	s_or_b64 exec, exec, s[0:1]
	v_cmp_le_u32_e32 vcc, s8, v207
	s_and_saveexec_b64 s[0:1], vcc
	s_cbranch_execnz .LBB0_3298

; __device__ __forceinline__ void select_group(unsigned char* ws, int r0, const bf16_t* __restrict__ kib, int n, float* sc, SelPre& pre, int nr0, const bf16_t* __restrict__ nkib, int nn) {
;     ...
;       for (int blk = 0; blk < 8; ++blk) {
;         if (blk * 8 < nreg) {
; #pragma unroll
;           for (int i = blk * 8; i < blk * 8 + 8; ++i) {
;             if (x[i] >= tau2) { selrow[pos] = (unsigned short)(i * 64 + lane); ++pos; }
;           }
;         }
.LBB0_3324:
	v_add_u32_e32 v16, 1, v166
	v_lshl_add_u32 v167, v166, 1, s100
	v_or_b32_e32 v194, 0x7c0, v114
	ds_write_b16 v167, v194
	v_mov_b32_e32 v166, v16

; __device__ __forceinline__ void select_group(unsigned char* ws, int r0, const bf16_t* __restrict__ kib, int n, float* sc, SelPre& pre, int nr0, const bf16_t* __restrict__ nkib, int nn) {
;     ...
;       for (int blk = 0; blk < 8; ++blk) {
;         if (blk * 8 < nreg) {
; #pragma unroll
;           for (int i = blk * 8; i < blk * 8 + 8; ++i) {
;             if (x[i] >= tau2) { selrow[pos] = (unsigned short)(i * 64 + lane); ++pos; }
;           }
;         }
.LBB0_3327:
	v_cmp_le_u32_e32 vcc, s8, v187
	s_and_saveexec_b64 s[0:1], vcc
	s_cbranch_execz .LBB0_3353
	v_add_u32_e32 v16, 1, v166
	v_lshl_add_u32 v167, v166, 1, s100
	v_or_b32_e32 v186, 0xa00, v114
	ds_write_b16 v167, v186
	v_mov_b32_e32 v166, v16
	s_or_b64 exec, exec, s[0:1]
	v_cmp_le_u32_e32 vcc, s8, v185
	s_and_saveexec_b64 s[0:1], vcc
	s_cbranch_execnz .LBB0_3354

; __device__ __forceinline__ void select_group(unsigned char* ws, int r0, const bf16_t* __restrict__ kib, int n, float* sc, SelPre& pre, int nr0, const bf16_t* __restrict__ nkib, int nn) {
;     ...
;       for (int blk = 0; blk < 8; ++blk) {
;         if (blk * 8 < nreg) {
; #pragma unroll
;           for (int i = blk * 8; i < blk * 8 + 8; ++i) {
;             if (x[i] >= tau2) { selrow[pos] = (unsigned short)(i * 64 + lane); ++pos; }
;           }
;         }
.LBB0_3330:
	v_add_u32_e32 v16, 1, v166
	v_lshl_add_u32 v167, v166, 1, s100
	v_or_b32_e32 v184, 0xa80, v114
	ds_write_b16 v167, v184
	v_mov_b32_e32 v166, v16
	s_or_b64 exec, exec, s[0:1]
	v_cmp_le_u32_e32 vcc, s8, v183
	s_and_saveexec_b64 s[0:1], vcc
	s_cbranch_execnz .LBB0_3356

; __device__ __forceinline__ void select_group(unsigned char* ws, int r0, const bf16_t* __restrict__ kib, int n, float* sc, SelPre& pre, int nr0, const bf16_t* __restrict__ nkib, int nn) {
;     ...
;       for (int blk = 0; blk < 8; ++blk) {
;         if (blk * 8 < nreg) {
; #pragma unroll
;           for (int i = blk * 8; i < blk * 8 + 8; ++i) {
;             if (x[i] >= tau2) { selrow[pos] = (unsigned short)(i * 64 + lane); ++pos; }
;           }
;         }
.LBB0_3332:
	v_add_u32_e32 v16, 1, v166
	v_lshl_add_u32 v167, v166, 1, s100
	v_or_b32_e32 v182, 0xb00, v114
	ds_write_b16 v167, v182
	v_mov_b32_e32 v166, v16
	s_or_b64 exec, exec, s[0:1]
	v_cmp_le_u32_e32 vcc, s8, v181
	s_and_saveexec_b64 s[0:1], vcc
	s_cbranch_execnz .LBB0_3358

; __device__ __forceinline__ void select_group(unsigned char* ws, int r0, const bf16_t* __restrict__ kib, int n, float* sc, SelPre& pre, int nr0, const bf16_t* __restrict__ nkib, int nn) {
;     ...
;       for (int blk = 0; blk < 8; ++blk) {
;         if (blk * 8 < nreg) {
; #pragma unroll
;           for (int i = blk * 8; i < blk * 8 + 8; ++i) {
;             if (x[i] >= tau2) { selrow[pos] = (unsigned short)(i * 64 + lane); ++pos; }
;           }
;         }
.LBB0_3334:
	v_add_u32_e32 v16, 1, v166
	v_lshl_add_u32 v167, v166, 1, s100
	v_or_b32_e32 v180, 0xb80, v114
	ds_write_b16 v167, v180
	v_mov_b32_e32 v166, v16
	s_or_b64 exec, exec, s[0:1]
	v_cmp_le_u32_e32 vcc, s8, v178
	s_and_saveexec_b64 s[0:1], vcc
	s_cbranch_execnz .LBB0_3360
	s_branch .LBB0_3361

; __device__ __forceinline__ void select_group(unsigned char* ws, int r0, const bf16_t* __restrict__ kib, int n, float* sc, SelPre& pre, int nr0, const bf16_t* __restrict__ nkib, int nn) {
;     ...
;       for (int blk = 0; blk < 8; ++blk) {
;         if (blk * 8 < nreg) {
; #pragma unroll
;           for (int i = blk * 8; i < blk * 8 + 8; ++i) {
;             if (x[i] >= tau2) { selrow[pos] = (unsigned short)(i * 64 + lane); ++pos; }
;           }
;         }
.LBB0_3336:
	v_add_u32_e32 v16, 1, v166
	v_lshl_add_u32 v167, v166, 1, s100
	v_or_b32_e32 v193, 0x840, v114
	ds_write_b16 v167, v193
	v_mov_b32_e32 v166, v16
	s_or_b64 exec, exec, s[0:1]
	v_cmp_le_u32_e32 vcc, s8, v192
	s_and_saveexec_b64 s[0:1], vcc
	s_cbranch_execnz .LBB0_3312

; __device__ __forceinline__ void select_group(unsigned char* ws, int r0, const bf16_t* __restrict__ kib, int n, float* sc, SelPre& pre, int nr0, const bf16_t* __restrict__ nkib, int nn) {
;     ...
;       for (int blk = 0; blk < 8; ++blk) {
;         if (blk * 8 < nreg) {
; #pragma unroll
;           for (int i = blk * 8; i < blk * 8 + 8; ++i) {
;             if (x[i] >= tau2) { selrow[pos] = (unsigned short)(i * 64 + lane); ++pos; }
;           }
;         }
.LBB0_3338:
	v_add_u32_e32 v16, 1, v166
	v_lshl_add_u32 v167, v166, 1, s100
	v_or_b32_e32 v191, 0x8c0, v114
	ds_write_b16 v167, v191
	v_mov_b32_e32 v166, v16
	s_or_b64 exec, exec, s[0:1]
	v_cmp_le_u32_e32 vcc, s8, v190
	s_and_saveexec_b64 s[0:1], vcc
	s_cbranch_execnz .LBB0_3314

; __device__ __forceinline__ void select_group(unsigned char* ws, int r0, const bf16_t* __restrict__ kib, int n, float* sc, SelPre& pre, int nr0, const bf16_t* __restrict__ nkib, int nn) {
;     ...
;       for (int blk = 0; blk < 8; ++blk) {
;         if (blk * 8 < nreg) {
; #pragma unroll
;           for (int i = blk * 8; i < blk * 8 + 8; ++i) {
;             if (x[i] >= tau2) { selrow[pos] = (unsigned short)(i * 64 + lane); ++pos; }
;           }
;         }
.LBB0_3340:
	v_add_u32_e32 v16, 1, v166
	v_lshl_add_u32 v167, v166, 1, s100
	v_or_b32_e32 v189, 0x940, v114
	ds_write_b16 v167, v189
	v_mov_b32_e32 v166, v16
	s_or_b64 exec, exec, s[0:1]
	v_cmp_le_u32_e32 vcc, s8, v188
	s_and_saveexec_b64 s[0:1], vcc
	s_cbranch_execnz .LBB0_3316

; __device__ __forceinline__ void select_group(unsigned char* ws, int r0, const bf16_t* __restrict__ kib, int n, float* sc, SelPre& pre, int nr0, const bf16_t* __restrict__ nkib, int nn) {
;     ...
;       for (int blk = 0; blk < 8; ++blk) {
;         if (blk * 8 < nreg) {
; #pragma unroll
;           for (int i = blk * 8; i < blk * 8 + 8; ++i) {
;             if (x[i] >= tau2) { selrow[pos] = (unsigned short)(i * 64 + lane); ++pos; }
;           }
;         }
;       }
.LBB0_3342:
	v_add_u32_e32 v16, 1, v166
	v_lshl_add_u32 v167, v166, 1, s100
	v_or_b32_e32 v186, 0x9c0, v114
	ds_write_b16 v167, v186
	v_mov_b32_e32 v166, v16

; __device__ __forceinline__ void select_group(unsigned char* ws, int r0, const bf16_t* __restrict__ kib, int n, float* sc, SelPre& pre, int nr0, const bf16_t* __restrict__ nkib, int nn) {
;     ...
;       for (int blk = 0; blk < 8; ++blk) {
;         if (blk * 8 < nreg) {
; #pragma unroll
;           for (int i = blk * 8; i < blk * 8 + 8; ++i) {
;             if (x[i] >= tau2) { selrow[pos] = (unsigned short)(i * 64 + lane); ++pos; }
;           }
;         }
;       }
.LBB0_3345:
	v_cmp_le_u32_e32 vcc, s8, v179
	s_and_saveexec_b64 s[0:1], vcc
	s_cbranch_execz .LBB0_3363
	v_add_u32_e32 v16, 1, v166
	v_lshl_add_u32 v167, v166, 1, s100
	v_or_b32_e32 v178, 0xc00, v114
	ds_write_b16 v167, v178
	v_mov_b32_e32 v166, v16
	s_or_b64 exec, exec, s[0:1]
	v_cmp_le_u32_e32 vcc, s8, v177
	s_and_saveexec_b64 s[0:1], vcc
	s_cbranch_execnz .LBB0_3364

; __device__ __forceinline__ void select_group(unsigned char* ws, int r0, const bf16_t* __restrict__ kib, int n, float* sc, SelPre& pre, int nr0, const bf16_t* __restrict__ nkib, int nn) {
;     ...
;       for (int blk = 0; blk < 8; ++blk) {
;         if (blk * 8 < nreg) {
; #pragma unroll
;           for (int i = blk * 8; i < blk * 8 + 8; ++i) {
;             if (x[i] >= tau2) { selrow[pos] = (unsigned short)(i * 64 + lane); ++pos; }
;           }
;         }
;       }
.LBB0_3348:
	v_add_u32_e32 v16, 1, v166
	v_lshl_add_u32 v167, v166, 1, s100
	v_or_b32_e32 v176, 0xc80, v114
	ds_write_b16 v167, v176
	v_mov_b32_e32 v166, v16
	s_or_b64 exec, exec, s[0:1]
	v_cmp_le_u32_e32 vcc, s8, v175
	s_and_saveexec_b64 s[0:1], vcc
	s_cbranch_execnz .LBB0_3366

; __device__ __forceinline__ void select_group(unsigned char* ws, int r0, const bf16_t* __restrict__ kib, int n, float* sc, SelPre& pre, int nr0, const bf16_t* __restrict__ nkib, int nn) {
;     ...
;       for (int blk = 0; blk < 8; ++blk) {
;         if (blk * 8 < nreg) {
; #pragma unroll
;           for (int i = blk * 8; i < blk * 8 + 8; ++i) {
;             if (x[i] >= tau2) { selrow[pos] = (unsigned short)(i * 64 + lane); ++pos; }
;           }
;         }
;       }
.LBB0_3350:
	v_add_u32_e32 v16, 1, v166
	v_lshl_add_u32 v167, v166, 1, s100
	v_or_b32_e32 v174, 0xd00, v114
	ds_write_b16 v167, v174
	v_mov_b32_e32 v166, v16
	s_or_b64 exec, exec, s[0:1]
	v_cmp_le_u32_e32 vcc, s8, v173
	s_and_saveexec_b64 s[0:1], vcc
	s_cbranch_execnz .LBB0_3368

; __device__ __forceinline__ void select_group(unsigned char* ws, int r0, const bf16_t* __restrict__ kib, int n, float* sc, SelPre& pre, int nr0, const bf16_t* __restrict__ nkib, int nn) {
;     ...
;       for (int blk = 0; blk < 8; ++blk) {
;         if (blk * 8 < nreg) {
; #pragma unroll
;           for (int i = blk * 8; i < blk * 8 + 8; ++i) {
;             if (x[i] >= tau2) { selrow[pos] = (unsigned short)(i * 64 + lane); ++pos; }
;           }
;         }
;       }
.LBB0_3352:
	v_add_u32_e32 v16, 1, v166
	v_lshl_add_u32 v167, v166, 1, s100
	v_or_b32_e32 v172, 0xd80, v114
	ds_write_b16 v167, v172
	v_mov_b32_e32 v166, v16
	s_or_b64 exec, exec, s[0:1]
	v_cmp_le_u32_e32 vcc, s8, v115
	s_and_saveexec_b64 s[0:1], vcc
	s_cbranch_execnz .LBB0_3370
	s_branch .LBB0_3371

; __device__ __forceinline__ void select_group(unsigned char* ws, int r0, const bf16_t* __restrict__ kib, int n, float* sc, SelPre& pre, int nr0, const bf16_t* __restrict__ nkib, int nn) {
;     ...
;       for (int blk = 0; blk < 8; ++blk) {
;         if (blk * 8 < nreg) {
; #pragma unroll
;           for (int i = blk * 8; i < blk * 8 + 8; ++i) {
;             if (x[i] >= tau2) { selrow[pos] = (unsigned short)(i * 64 + lane); ++pos; }
;           }
;         }
;       }
.LBB0_3354:
	v_add_u32_e32 v16, 1, v166
	v_lshl_add_u32 v167, v166, 1, s100
	v_or_b32_e32 v185, 0xa40, v114
	ds_write_b16 v167, v185
	v_mov_b32_e32 v166, v16
	s_or_b64 exec, exec, s[0:1]
	v_cmp_le_u32_e32 vcc, s8, v184
	s_and_saveexec_b64 s[0:1], vcc
	s_cbranch_execnz .LBB0_3330

; __device__ __forceinline__ void select_group(unsigned char* ws, int r0, const bf16_t* __restrict__ kib, int n, float* sc, SelPre& pre, int nr0, const bf16_t* __restrict__ nkib, int nn) {
;     ...
;       for (int blk = 0; blk < 8; ++blk) {
;         if (blk * 8 < nreg) {
; #pragma unroll
;           for (int i = blk * 8; i < blk * 8 + 8; ++i) {
;             if (x[i] >= tau2) { selrow[pos] = (unsigned short)(i * 64 + lane); ++pos; }
;           }
;         }
;       }
.LBB0_3356:
	v_add_u32_e32 v16, 1, v166
	v_lshl_add_u32 v167, v166, 1, s100
	v_or_b32_e32 v183, 0xac0, v114
	ds_write_b16 v167, v183
	v_mov_b32_e32 v166, v16
	s_or_b64 exec, exec, s[0:1]
	v_cmp_le_u32_e32 vcc, s8, v182
	s_and_saveexec_b64 s[0:1], vcc
	s_cbranch_execnz .LBB0_3332

; __device__ __forceinline__ void select_group(unsigned char* ws, int r0, const bf16_t* __restrict__ kib, int n, float* sc, SelPre& pre, int nr0, const bf16_t* __restrict__ nkib, int nn) {
;     ...
;       for (int blk = 0; blk < 8; ++blk) {
;         if (blk * 8 < nreg) {
; #pragma unroll
;           for (int i = blk * 8; i < blk * 8 + 8; ++i) {
;             if (x[i] >= tau2) { selrow[pos] = (unsigned short)(i * 64 + lane); ++pos; }
;           }
;         }
;       }
.LBB0_3358:
	v_add_u32_e32 v16, 1, v166
	v_lshl_add_u32 v167, v166, 1, s100
	v_or_b32_e32 v181, 0xb40, v114
	ds_write_b16 v167, v181
	v_mov_b32_e32 v166, v16
	s_or_b64 exec, exec, s[0:1]
	v_cmp_le_u32_e32 vcc, s8, v180
	s_and_saveexec_b64 s[0:1], vcc
	s_cbranch_execnz .LBB0_3334

; __device__ __forceinline__ void select_group(unsigned char* ws, int r0, const bf16_t* __restrict__ kib, int n, float* sc, SelPre& pre, int nr0, const bf16_t* __restrict__ nkib, int nn) {
;     ...
;       for (int blk = 0; blk < 8; ++blk) {
;         if (blk * 8 < nreg) {
; #pragma unroll
;           for (int i = blk * 8; i < blk * 8 + 8; ++i) {
;             if (x[i] >= tau2) { selrow[pos] = (unsigned short)(i * 64 + lane); ++pos; }
;           }
;         }
;       }
.LBB0_3360:
	v_add_u32_e32 v16, 1, v166
	v_lshl_add_u32 v167, v166, 1, s100
	v_or_b32_e32 v178, 0xbc0, v114
	ds_write_b16 v167, v178
	v_mov_b32_e32 v166, v16

; __device__ __forceinline__ void select_group(unsigned char* ws, int r0, const bf16_t* __restrict__ kib, int n, float* sc, SelPre& pre, int nr0, const bf16_t* __restrict__ nkib, int nn) {
;     ...
;       for (int blk = 0; blk < 8; ++blk) {
;         if (blk * 8 < nreg) {
; #pragma unroll
;           for (int i = blk * 8; i < blk * 8 + 8; ++i) {
;             if (x[i] >= tau2) { selrow[pos] = (unsigned short)(i * 64 + lane); ++pos; }
;           }
;         }
;       }
.LBB0_3364:
	v_add_u32_e32 v16, 1, v166
	v_lshl_add_u32 v167, v166, 1, s100
	v_or_b32_e32 v177, 0xc40, v114
	ds_write_b16 v167, v177
	v_mov_b32_e32 v166, v16
	s_or_b64 exec, exec, s[0:1]
	v_cmp_le_u32_e32 vcc, s8, v176
	s_and_saveexec_b64 s[0:1], vcc
	s_cbranch_execnz .LBB0_3348

; __device__ __forceinline__ void select_group(unsigned char* ws, int r0, const bf16_t* __restrict__ kib, int n, float* sc, SelPre& pre, int nr0, const bf16_t* __restrict__ nkib, int nn) {
;     ...
;       for (int blk = 0; blk < 8; ++blk) {
;         if (blk * 8 < nreg) {
; #pragma unroll
;           for (int i = blk * 8; i < blk * 8 + 8; ++i) {
;             if (x[i] >= tau2) { selrow[pos] = (unsigned short)(i * 64 + lane); ++pos; }
;           }
;         }
;       }
.LBB0_3366:
	v_add_u32_e32 v16, 1, v166
	v_lshl_add_u32 v167, v166, 1, s100
	v_or_b32_e32 v175, 0xcc0, v114
	ds_write_b16 v167, v175
	v_mov_b32_e32 v166, v16
	s_or_b64 exec, exec, s[0:1]
	v_cmp_le_u32_e32 vcc, s8, v174
	s_and_saveexec_b64 s[0:1], vcc
	s_cbranch_execnz .LBB0_3350

; __device__ __forceinline__ void select_group(unsigned char* ws, int r0, const bf16_t* __restrict__ kib, int n, float* sc, SelPre& pre, int nr0, const bf16_t* __restrict__ nkib, int nn) {
;     ...
;       for (int blk = 0; blk < 8; ++blk) {
;         if (blk * 8 < nreg) {
; #pragma unroll
;           for (int i = blk * 8; i < blk * 8 + 8; ++i) {
;             if (x[i] >= tau2) { selrow[pos] = (unsigned short)(i * 64 + lane); ++pos; }
;           }
;         }
;       }
.LBB0_3368:
	v_add_u32_e32 v16, 1, v166
	v_lshl_add_u32 v167, v166, 1, s100
	v_or_b32_e32 v173, 0xd40, v114
	ds_write_b16 v167, v173
	v_mov_b32_e32 v166, v16
	s_or_b64 exec, exec, s[0:1]
	v_cmp_le_u32_e32 vcc, s8, v172
	s_and_saveexec_b64 s[0:1], vcc
	s_cbranch_execnz .LBB0_3352

; __device__ __forceinline__ void select_group(unsigned char* ws, int r0, const bf16_t* __restrict__ kib, int n, float* sc, SelPre& pre, int nr0, const bf16_t* __restrict__ nkib, int nn) {
;     ...
;       for (int blk = 0; blk < 8; ++blk) {
;         if (blk * 8 < nreg) {
; #pragma unroll
;           for (int i = blk * 8; i < blk * 8 + 8; ++i) {
;             if (x[i] >= tau2) { selrow[pos] = (unsigned short)(i * 64 + lane); ++pos; }
;           }
;         }
;       }
.LBB0_3370:
	v_add_u32_e32 v16, 1, v166
	v_lshl_add_u32 v167, v166, 1, s100
	v_or_b32_e32 v115, 0xdc0, v114
	ds_write_b16 v167, v115
	v_mov_b32_e32 v166, v16

; __device__ __forceinline__ void select_group(unsigned char* ws, int r0, const bf16_t* __restrict__ kib, int n, float* sc, SelPre& pre, int nr0, const bf16_t* __restrict__ nkib, int nn) {
;     ...
;       for (int blk = 0; blk < 8; ++blk) {
;         if (blk * 8 < nreg) {
; #pragma unroll
;           for (int i = blk * 8; i < blk * 8 + 8; ++i) {
;             if (x[i] >= tau2) { selrow[pos] = (unsigned short)(i * 64 + lane); ++pos; }
;           }
;         }
;       }
.LBB0_3372:
	v_cmp_le_u32_e32 vcc, s8, v243
	s_and_saveexec_b64 s[0:1], vcc
	s_cbranch_execz .LBB0_3380
	v_add_u32_e32 v16, 1, v166
	v_lshl_add_u32 v167, v166, 1, s100
	v_or_b32_e32 v115, 0xe00, v114
	ds_write_b16 v167, v115
	v_mov_b32_e32 v166, v16
	s_or_b64 exec, exec, s[0:1]
	v_cmp_le_u32_e32 vcc, s8, v242
	s_and_saveexec_b64 s[0:1], vcc
	s_cbranch_execnz .LBB0_3381

; __device__ __forceinline__ void select_group(unsigned char* ws, int r0, const bf16_t* __restrict__ kib, int n, float* sc, SelPre& pre, int nr0, const bf16_t* __restrict__ nkib, int nn) {
;     ...
;       for (int blk = 0; blk < 8; ++blk) {
;         if (blk * 8 < nreg) {
; #pragma unroll
;           for (int i = blk * 8; i < blk * 8 + 8; ++i) {
;             if (x[i] >= tau2) { selrow[pos] = (unsigned short)(i * 64 + lane); ++pos; }
;           }
;         }
;       }
.LBB0_3375:
	v_add_u32_e32 v16, 1, v166
	v_lshl_add_u32 v167, v166, 1, s100
	v_or_b32_e32 v115, 0xe80, v114
	ds_write_b16 v167, v115
	v_mov_b32_e32 v166, v16
	s_or_b64 exec, exec, s[0:1]
	v_cmp_le_u32_e32 vcc, s8, v240
	s_and_saveexec_b64 s[0:1], vcc
	s_cbranch_execnz .LBB0_3383

; __device__ __forceinline__ void select_group(unsigned char* ws, int r0, const bf16_t* __restrict__ kib, int n, float* sc, SelPre& pre, int nr0, const bf16_t* __restrict__ nkib, int nn) {
;     ...
;       for (int blk = 0; blk < 8; ++blk) {
;         if (blk * 8 < nreg) {
; #pragma unroll
;           for (int i = blk * 8; i < blk * 8 + 8; ++i) {
;             if (x[i] >= tau2) { selrow[pos] = (unsigned short)(i * 64 + lane); ++pos; }
;           }
;         }
;       }
.LBB0_3377:
	v_add_u32_e32 v16, 1, v166
	v_lshl_add_u32 v167, v166, 1, s100
	v_or_b32_e32 v115, 0xf00, v114
	ds_write_b16 v167, v115
	v_mov_b32_e32 v166, v16
	s_or_b64 exec, exec, s[0:1]
	v_cmp_le_u32_e32 vcc, s8, v170
	s_and_saveexec_b64 s[0:1], vcc
	s_cbranch_execnz .LBB0_3385

; __device__ __forceinline__ void select_group(unsigned char* ws, int r0, const bf16_t* __restrict__ kib, int n, float* sc, SelPre& pre, int nr0, const bf16_t* __restrict__ nkib, int nn) {
;     ...
;       for (int blk = 0; blk < 8; ++blk) {
;         if (blk * 8 < nreg) {
; #pragma unroll
;           for (int i = blk * 8; i < blk * 8 + 8; ++i) {
;             if (x[i] >= tau2) { selrow[pos] = (unsigned short)(i * 64 + lane); ++pos; }
;           }
;         }
;       }
.LBB0_3379:
	v_add_u32_e32 v16, 1, v166
	v_lshl_add_u32 v167, v166, 1, s100
	v_or_b32_e32 v115, 0xf80, v114
	ds_write_b16 v167, v115
	v_mov_b32_e32 v166, v16
	s_or_b64 exec, exec, s[0:1]
	v_cmp_le_u32_e32 vcc, s8, v168
	s_and_saveexec_b64 s[0:1], vcc
	s_cbranch_execnz .LBB0_3387
	s_branch .LBB0_3388

; __device__ __forceinline__ void select_group(unsigned char* ws, int r0, const bf16_t* __restrict__ kib, int n, float* sc, SelPre& pre, int nr0, const bf16_t* __restrict__ nkib, int nn) {
;     ...
;       for (int blk = 0; blk < 8; ++blk) {
;         if (blk * 8 < nreg) {
; #pragma unroll
;           for (int i = blk * 8; i < blk * 8 + 8; ++i) {
;             if (x[i] >= tau2) { selrow[pos] = (unsigned short)(i * 64 + lane); ++pos; }
;           }
;         }
;       }
.LBB0_3381:
	v_add_u32_e32 v16, 1, v166
	v_lshl_add_u32 v167, v166, 1, s100
	v_or_b32_e32 v115, 0xe40, v114
	ds_write_b16 v167, v115
	v_mov_b32_e32 v166, v16
	s_or_b64 exec, exec, s[0:1]
	v_cmp_le_u32_e32 vcc, s8, v241
	s_and_saveexec_b64 s[0:1], vcc
	s_cbranch_execnz .LBB0_3375

; __device__ __forceinline__ void select_group(unsigned char* ws, int r0, const bf16_t* __restrict__ kib, int n, float* sc, SelPre& pre, int nr0, const bf16_t* __restrict__ nkib, int nn) {
;     ...
;       for (int blk = 0; blk < 8; ++blk) {
;         if (blk * 8 < nreg) {
; #pragma unroll
;           for (int i = blk * 8; i < blk * 8 + 8; ++i) {
;             if (x[i] >= tau2) { selrow[pos] = (unsigned short)(i * 64 + lane); ++pos; }
;           }
;         }
;       }
.LBB0_3383:
	v_add_u32_e32 v16, 1, v166
	v_lshl_add_u32 v167, v166, 1, s100
	v_or_b32_e32 v115, 0xec0, v114
	ds_write_b16 v167, v115
	v_mov_b32_e32 v166, v16
	s_or_b64 exec, exec, s[0:1]
	v_cmp_le_u32_e32 vcc, s8, v171
	s_and_saveexec_b64 s[0:1], vcc
	s_cbranch_execnz .LBB0_3377

; __device__ __forceinline__ void select_group(unsigned char* ws, int r0, const bf16_t* __restrict__ kib, int n, float* sc, SelPre& pre, int nr0, const bf16_t* __restrict__ nkib, int nn) {
;     ...
;       for (int blk = 0; blk < 8; ++blk) {
;         if (blk * 8 < nreg) {
; #pragma unroll
;           for (int i = blk * 8; i < blk * 8 + 8; ++i) {
;             if (x[i] >= tau2) { selrow[pos] = (unsigned short)(i * 64 + lane); ++pos; }
;           }
;         }
;       }
.LBB0_3385:
	v_add_u32_e32 v16, 1, v166
	v_lshl_add_u32 v167, v166, 1, s100
	v_or_b32_e32 v115, 0xf40, v114
	ds_write_b16 v167, v115
	v_mov_b32_e32 v166, v16
	s_or_b64 exec, exec, s[0:1]
	v_cmp_le_u32_e32 vcc, s8, v169
	s_and_saveexec_b64 s[0:1], vcc
	s_cbranch_execnz .LBB0_3379

; __device__ __forceinline__ void select_group(unsigned char* ws, int r0, const bf16_t* __restrict__ kib, int n, float* sc, SelPre& pre, int nr0, const bf16_t* __restrict__ nkib, int nn) {
;     ...
;       for (int blk = 0; blk < 8; ++blk) {
;         if (blk * 8 < nreg) {
; #pragma unroll
;           for (int i = blk * 8; i < blk * 8 + 8; ++i) {
;             if (x[i] >= tau2) { selrow[pos] = (unsigned short)(i * 64 + lane); ++pos; }
;           }
;         }
;       }
.LBB0_3387:
	v_lshl_add_u32 v167, v166, 1, s100
	v_or_b32_e32 v16, 0xfc0, v114
	ds_write_b16 v167, v16

; __device__ __forceinline__ void select_group(unsigned char* ws, int r0, const bf16_t* __restrict__ kib, int n, float* sc, SelPre& pre, int nr0, const bf16_t* __restrict__ nkib, int nn) {
;     ...
;       int pos = incl - myc;
; #pragma unroll
;       for (int blk = 0; blk < 8; ++blk) {
;         if (blk * 8 < nreg) {
; #pragma unroll
;           for (int i = blk * 8; i < blk * 8 + 8; ++i) {
;             if (x[i] >= tau2) { selrow[pos] = (unsigned short)(i * 64 + lane); ++pos; }
;           }
;         }
;       }
.Lsel_flush:
	s_waitcnt lgkmcnt(0)
	v_lshl_add_u32 v16, v252, 3, s100
	ds_read_b64 v[166:167], v16
	v_lshlrev_b32_e32 v16, 3, v252
	v_lshl_add_u64 v[164:165], v[164:165], 0, v[16:17]
	s_waitcnt lgkmcnt(0)
	global_store_dwordx2 v[164:165], v[166:167], off
